# GEMM unit transitions: accumulators cleared with v_mov_b64 inline 0 (64 instructions) instead of 128 v_mov_b32
# speedup vs baseline: 1.0015x; 1.0015x over previous
.LBB0_172:
	s_ashr_i32 s21, s20, 31
	s_lshl_b64 s[22:23], s[20:21], 20
	s_add_u32 s22, s46, s22
	s_addc_u32 s23, s47, s23
	s_and_b64 s[24:25], s[0:1], exec
	s_cselect_b32 s21, s23, s29
	s_cselect_b32 s33, s22, s28
	s_ashr_i32 s19, s18, 31
	s_lshl_b64 s[24:25], s[18:19], 20
	s_add_u32 s24, s78, s24
	s_addc_u32 s25, s79, s25
	s_and_b64 s[34:35], s[0:1], exec
	s_cselect_b32 s19, s25, s31
	s_cselect_b32 s42, s24, s30
	s_add_u32 s28, s28, 0x80080
	s_addc_u32 s29, s29, 0
	s_add_u32 s52, s30, 0x100
	v_mov_b32_e32 v0, 0
	s_addc_u32 s53, s31, 0
	s_mov_b32 s54, -2
	v_mov_b32_e32 v1, 0
	v_mov_b64_e32 v[2:3], 0
	v_mov_b64_e32 v[8:9], 0
	v_mov_b64_e32 v[10:11], 0
	v_mov_b64_e32 v[16:17], 0
	v_mov_b64_e32 v[18:19], 0
	v_mov_b64_e32 v[24:25], 0
	v_mov_b64_e32 v[26:27], 0
	v_mov_b64_e32 v[32:33], 0
	v_mov_b64_e32 v[34:35], 0
	v_mov_b64_e32 v[40:41], 0
	v_mov_b64_e32 v[42:43], 0
	v_mov_b64_e32 v[48:49], 0
	v_mov_b64_e32 v[50:51], 0
	v_mov_b64_e32 v[56:57], 0
	v_mov_b64_e32 v[58:59], 0
	v_mov_b64_e32 v[4:5], 0
	v_mov_b64_e32 v[6:7], 0
	v_mov_b64_e32 v[12:13], 0
	v_mov_b64_e32 v[14:15], 0
	v_mov_b64_e32 v[20:21], 0
	v_mov_b64_e32 v[22:23], 0
	v_mov_b64_e32 v[28:29], 0
	v_mov_b64_e32 v[30:31], 0
	v_mov_b64_e32 v[36:37], 0
	v_mov_b64_e32 v[38:39], 0
	v_mov_b64_e32 v[44:45], 0
	v_mov_b64_e32 v[46:47], 0
	v_mov_b64_e32 v[52:53], 0
	v_mov_b64_e32 v[54:55], 0
	v_mov_b64_e32 v[60:61], 0
	v_mov_b64_e32 v[62:63], 0
	v_mov_b64_e32 v[64:65], 0
	v_mov_b64_e32 v[66:67], 0
	v_mov_b64_e32 v[72:73], 0
	v_mov_b64_e32 v[74:75], 0
	v_mov_b64_e32 v[80:81], 0
	v_mov_b64_e32 v[82:83], 0
	v_mov_b64_e32 v[88:89], 0
	v_mov_b64_e32 v[90:91], 0
	v_mov_b64_e32 v[96:97], 0
	v_mov_b64_e32 v[98:99], 0
	v_mov_b64_e32 v[104:105], 0
	v_mov_b64_e32 v[106:107], 0
	v_mov_b64_e32 v[112:113], 0
	v_mov_b64_e32 v[114:115], 0
	v_mov_b64_e32 v[120:121], 0
	v_mov_b64_e32 v[122:123], 0
	v_mov_b64_e32 v[68:69], 0
	v_mov_b64_e32 v[70:71], 0
	v_mov_b64_e32 v[76:77], 0
	v_mov_b64_e32 v[78:79], 0
	v_mov_b64_e32 v[84:85], 0
	v_mov_b64_e32 v[86:87], 0
	v_mov_b64_e32 v[92:93], 0
	v_mov_b64_e32 v[94:95], 0
	v_mov_b64_e32 v[100:101], 0
	v_mov_b64_e32 v[102:103], 0
	v_mov_b64_e32 v[108:109], 0
	v_mov_b64_e32 v[110:111], 0
	v_mov_b64_e32 v[116:117], 0
	v_mov_b64_e32 v[118:119], 0
	v_mov_b64_e32 v[124:125], 0
	v_mov_b64_e32 v[126:127], 0

.LBB0_256:
	s_add_u32 s22, s22, 0xc000
	s_addc_u32 s23, s23, 0
	s_add_u32 s44, s0, 0x10000
	v_mov_b32_e32 v0, 0
	s_addc_u32 s45, s1, 0
	s_mov_b32 s50, -2
	s_waitcnt lgkmcnt(0)
	v_mov_b32_e32 v1, 0
	v_mov_b64_e32 v[2:3], 0
	v_mov_b64_e32 v[4:5], 0
	v_mov_b64_e32 v[6:7], 0
	v_mov_b64_e32 v[16:17], 0
	v_mov_b64_e32 v[18:19], 0
	v_mov_b64_e32 v[20:21], 0
	v_mov_b64_e32 v[22:23], 0
	v_mov_b64_e32 v[32:33], 0
	v_mov_b64_e32 v[34:35], 0
	v_mov_b64_e32 v[36:37], 0
	v_mov_b64_e32 v[38:39], 0
	v_mov_b64_e32 v[48:49], 0
	v_mov_b64_e32 v[50:51], 0
	v_mov_b64_e32 v[52:53], 0
	v_mov_b64_e32 v[54:55], 0
	v_mov_b64_e32 v[8:9], 0
	v_mov_b64_e32 v[10:11], 0
	v_mov_b64_e32 v[12:13], 0
	v_mov_b64_e32 v[14:15], 0
	v_mov_b64_e32 v[24:25], 0
	v_mov_b64_e32 v[26:27], 0
	v_mov_b64_e32 v[28:29], 0
	v_mov_b64_e32 v[30:31], 0
	v_mov_b64_e32 v[40:41], 0
	v_mov_b64_e32 v[42:43], 0
	v_mov_b64_e32 v[44:45], 0
	v_mov_b64_e32 v[46:47], 0
	v_mov_b64_e32 v[56:57], 0
	v_mov_b64_e32 v[58:59], 0
	v_mov_b64_e32 v[60:61], 0
	v_mov_b64_e32 v[62:63], 0
	v_mov_b64_e32 v[64:65], 0
	v_mov_b64_e32 v[66:67], 0
	v_mov_b64_e32 v[68:69], 0
	v_mov_b64_e32 v[70:71], 0
	v_mov_b64_e32 v[80:81], 0
	v_mov_b64_e32 v[82:83], 0
	v_mov_b64_e32 v[84:85], 0
	v_mov_b64_e32 v[86:87], 0
	v_mov_b64_e32 v[96:97], 0
	v_mov_b64_e32 v[98:99], 0
	v_mov_b64_e32 v[100:101], 0
	v_mov_b64_e32 v[102:103], 0
	v_mov_b64_e32 v[112:113], 0
	v_mov_b64_e32 v[114:115], 0
	v_mov_b64_e32 v[116:117], 0
	v_mov_b64_e32 v[118:119], 0
	v_mov_b64_e32 v[72:73], 0
	v_mov_b64_e32 v[74:75], 0
	v_mov_b64_e32 v[76:77], 0
	v_mov_b64_e32 v[78:79], 0
	v_mov_b64_e32 v[88:89], 0
	v_mov_b64_e32 v[90:91], 0
	v_mov_b64_e32 v[92:93], 0
	v_mov_b64_e32 v[94:95], 0
	v_mov_b64_e32 v[104:105], 0
	v_mov_b64_e32 v[106:107], 0
	v_mov_b64_e32 v[108:109], 0
	v_mov_b64_e32 v[110:111], 0
	v_mov_b64_e32 v[120:121], 0
	v_mov_b64_e32 v[122:123], 0
	v_mov_b64_e32 v[124:125], 0
	v_mov_b64_e32 v[126:127], 0

.LBB0_350:
	s_ashr_i32 s25, s24, 31
	s_lshl_b64 s[26:27], s[24:25], 20
	s_cmp_eq_u32 s63, 0
	s_cselect_b32 s25, s46, s39
	s_cselect_b32 s23, s47, s40
	s_cselect_b32 s36, s10, s46
	s_cselect_b32 s37, s11, s47
	s_add_u32 s26, s25, s26
	s_addc_u32 s27, s23, s27
	s_and_b64 s[28:29], s[4:5], exec
	s_cselect_b32 s25, s27, s7
	s_cselect_b32 s33, s26, s6
	s_ashr_i32 s23, s22, 31
	s_lshl_b64 s[28:29], s[22:23], 20
	s_add_u32 s28, s36, s28
	s_addc_u32 s29, s37, s29
	s_and_b64 s[36:37], s[4:5], exec
	s_cselect_b32 s23, s29, s1
	s_cselect_b32 s42, s28, s0
	s_add_u32 s6, s6, 0x80080
	s_addc_u32 s7, s7, 0
	s_add_u32 s43, s0, 0x100
	v_mov_b32_e32 v0, 0
	s_addc_u32 s64, s1, 0
	s_mov_b32 s65, -2
	v_mov_b32_e32 v1, 0
	v_mov_b64_e32 v[2:3], 0
	v_mov_b64_e32 v[4:5], 0
	v_mov_b64_e32 v[6:7], 0
	v_mov_b64_e32 v[16:17], 0
	v_mov_b64_e32 v[18:19], 0
	v_mov_b64_e32 v[20:21], 0
	v_mov_b64_e32 v[22:23], 0
	v_mov_b64_e32 v[32:33], 0
	v_mov_b64_e32 v[34:35], 0
	v_mov_b64_e32 v[36:37], 0
	v_mov_b64_e32 v[38:39], 0
	v_mov_b64_e32 v[48:49], 0
	v_mov_b64_e32 v[50:51], 0
	v_mov_b64_e32 v[52:53], 0
	v_mov_b64_e32 v[54:55], 0
	v_mov_b64_e32 v[8:9], 0
	v_mov_b64_e32 v[10:11], 0
	v_mov_b64_e32 v[12:13], 0
	v_mov_b64_e32 v[14:15], 0
	v_mov_b64_e32 v[24:25], 0
	v_mov_b64_e32 v[26:27], 0
	v_mov_b64_e32 v[28:29], 0
	v_mov_b64_e32 v[30:31], 0
	v_mov_b64_e32 v[40:41], 0
	v_mov_b64_e32 v[42:43], 0
	v_mov_b64_e32 v[44:45], 0
	v_mov_b64_e32 v[46:47], 0
	v_mov_b64_e32 v[56:57], 0
	v_mov_b64_e32 v[58:59], 0
	v_mov_b64_e32 v[60:61], 0
	v_mov_b64_e32 v[62:63], 0
	v_mov_b64_e32 v[64:65], 0
	v_mov_b64_e32 v[66:67], 0
	v_mov_b64_e32 v[68:69], 0
	v_mov_b64_e32 v[70:71], 0
	v_mov_b64_e32 v[80:81], 0
	v_mov_b64_e32 v[82:83], 0
	v_mov_b64_e32 v[84:85], 0
	v_mov_b64_e32 v[86:87], 0
	v_mov_b64_e32 v[96:97], 0
	v_mov_b64_e32 v[98:99], 0
	v_mov_b64_e32 v[100:101], 0
	v_mov_b64_e32 v[102:103], 0
	v_mov_b64_e32 v[112:113], 0
	v_mov_b64_e32 v[114:115], 0
	v_mov_b64_e32 v[116:117], 0
	v_mov_b64_e32 v[118:119], 0
	v_mov_b64_e32 v[72:73], 0
	v_mov_b64_e32 v[74:75], 0
	v_mov_b64_e32 v[76:77], 0
	v_mov_b64_e32 v[78:79], 0
	v_mov_b64_e32 v[88:89], 0
	v_mov_b64_e32 v[90:91], 0
	v_mov_b64_e32 v[92:93], 0
	v_mov_b64_e32 v[94:95], 0
	v_mov_b64_e32 v[104:105], 0
	v_mov_b64_e32 v[106:107], 0
	v_mov_b64_e32 v[108:109], 0
	v_mov_b64_e32 v[110:111], 0
	v_mov_b64_e32 v[120:121], 0
	v_mov_b64_e32 v[122:123], 0
	v_mov_b64_e32 v[124:125], 0
	v_mov_b64_e32 v[126:127], 0

.LBB0_629:
	s_ashr_i32 s23, s22, 31
	s_lshl_b64 s[24:25], s[22:23], 19
	s_add_u32 s24, s14, s24
	s_addc_u32 s25, s15, s25
	s_and_b64 s[26:27], s[4:5], exec
	s_cselect_b32 s23, s25, s29
	s_cselect_b32 s33, s24, s28
	s_ashr_i32 s21, s20, 31
	s_lshl_b64 s[26:27], s[20:21], 19
	s_add_u32 s26, s74, s26
	s_addc_u32 s27, s75, s27
	s_and_b64 s[30:31], s[4:5], exec
	s_cselect_b32 s21, s27, s1
	s_cselect_b32 s42, s26, s0
	s_add_u32 s28, s28, 0x40080
	s_addc_u32 s29, s29, 0
	s_add_u32 s52, s0, 0x100
	v_mov_b32_e32 v36, 0
	s_addc_u32 s53, s1, 0
	s_mov_b32 s54, -2
	v_mov_b32_e32 v37, v36
	v_mov_b32_e32 v38, v36
	v_mov_b32_e32 v39, v36
	v_mov_b32_e32 v44, v36
	v_mov_b32_e32 v45, v36
	v_mov_b32_e32 v46, v36
	v_mov_b32_e32 v47, v36
	v_mov_b32_e32 v48, v36
	v_mov_b32_e32 v49, v36
	v_mov_b32_e32 v50, v36
	v_mov_b32_e32 v51, v36
	v_mov_b32_e32 v60, v36
	v_mov_b32_e32 v61, v36
	v_mov_b32_e32 v62, v36
	v_mov_b32_e32 v63, v36
	v_mov_b32_e32 v64, v36
	v_mov_b32_e32 v65, v36
	v_mov_b32_e32 v66, v36
	v_mov_b32_e32 v67, v36
	v_mov_b32_e32 v76, v36
	v_mov_b32_e32 v77, v36
	v_mov_b32_e32 v78, v36
	v_mov_b32_e32 v79, v36
	s_waitcnt vmcnt(0)
	v_mov_b64_e32 v[80:81], 0
	v_mov_b64_e32 v[82:83], 0
	v_mov_b64_e32 v[92:93], 0
	v_mov_b64_e32 v[94:95], 0
	v_mov_b64_e32 v[32:33], 0
	v_mov_b64_e32 v[34:35], 0
	v_mov_b64_e32 v[40:41], 0
	v_mov_b64_e32 v[42:43], 0
	v_mov_b64_e32 v[52:53], 0
	v_mov_b64_e32 v[54:55], 0
	v_mov_b64_e32 v[56:57], 0
	v_mov_b64_e32 v[58:59], 0
	v_mov_b64_e32 v[68:69], 0
	v_mov_b64_e32 v[70:71], 0
	v_mov_b64_e32 v[72:73], 0
	v_mov_b64_e32 v[74:75], 0
	v_mov_b64_e32 v[84:85], 0
	v_mov_b64_e32 v[86:87], 0
	v_mov_b64_e32 v[88:89], 0
	v_mov_b64_e32 v[90:91], 0
	v_mov_b64_e32 v[96:97], 0
	v_mov_b64_e32 v[98:99], 0
	v_mov_b64_e32 v[108:109], 0
	v_mov_b64_e32 v[110:111], 0
	v_mov_b64_e32 v[112:113], 0
	v_mov_b64_e32 v[114:115], 0
	v_mov_b64_e32 v[124:125], 0
	v_mov_b64_e32 v[126:127], 0
	v_mov_b64_e32 v[128:129], 0
	v_mov_b64_e32 v[130:131], 0
	v_mov_b64_e32 v[140:141], 0
	v_mov_b64_e32 v[142:143], 0
	v_mov_b64_e32 v[144:145], 0
	v_mov_b64_e32 v[146:147], 0
	v_mov_b64_e32 v[156:157], 0
	v_mov_b64_e32 v[158:159], 0
	v_mov_b64_e32 v[100:101], 0
	v_mov_b64_e32 v[102:103], 0
	v_mov_b64_e32 v[104:105], 0
	v_mov_b64_e32 v[106:107], 0
	v_mov_b64_e32 v[116:117], 0
	v_mov_b64_e32 v[118:119], 0
	v_mov_b64_e32 v[120:121], 0
	v_mov_b64_e32 v[122:123], 0
	v_mov_b64_e32 v[132:133], 0
	v_mov_b64_e32 v[134:135], 0
	v_mov_b64_e32 v[136:137], 0
	v_mov_b64_e32 v[138:139], 0
	v_mov_b64_e32 v[148:149], 0
	v_mov_b64_e32 v[150:151], 0
	v_mov_b64_e32 v[152:153], 0
	v_mov_b64_e32 v[154:155], 0
	v_lshl_add_u32 v246, s6, 8, v194
	v_ashrrev_i32_e32 v247, 31, v246
	v_lshl_add_u64 v[246:247], v[246:247], 2, s[12:13]
	global_load_dword v238, v[246:247], off
	global_load_dword v239, v[246:247], off offset:64
	global_load_dword v240, v[246:247], off offset:128
	global_load_dword v241, v[246:247], off offset:192
	global_load_dword v242, v[246:247], off offset:512
	global_load_dword v243, v[246:247], off offset:576
	global_load_dword v244, v[246:247], off offset:640
	global_load_dword v245, v[246:247], off offset:704

.LBB0_726:
	s_add_u32 s18, s18, 0xc000
	s_addc_u32 s19, s19, 0
	s_add_u32 s42, s20, 0x10000
	v_mov_b32_e32 v0, 0
	s_addc_u32 s43, s21, 0
	s_mov_b32 s44, -2
	s_waitcnt lgkmcnt(0)
	v_mov_b32_e32 v1, 0
	v_mov_b64_e32 v[2:3], 0
	v_mov_b64_e32 v[4:5], 0
	v_mov_b64_e32 v[6:7], 0
	v_mov_b64_e32 v[16:17], 0
	v_mov_b64_e32 v[18:19], 0
	v_mov_b64_e32 v[20:21], 0
	v_mov_b64_e32 v[22:23], 0
	v_mov_b64_e32 v[32:33], 0
	v_mov_b64_e32 v[34:35], 0
	v_mov_b64_e32 v[36:37], 0
	v_mov_b64_e32 v[38:39], 0
	v_mov_b64_e32 v[48:49], 0
	v_mov_b64_e32 v[50:51], 0
	v_mov_b64_e32 v[52:53], 0
	v_mov_b64_e32 v[54:55], 0
	v_mov_b64_e32 v[8:9], 0
	v_mov_b64_e32 v[10:11], 0
	v_mov_b64_e32 v[12:13], 0
	v_mov_b64_e32 v[14:15], 0
	v_mov_b64_e32 v[24:25], 0
	v_mov_b64_e32 v[26:27], 0
	v_mov_b64_e32 v[28:29], 0
	v_mov_b64_e32 v[30:31], 0
	v_mov_b64_e32 v[40:41], 0
	v_mov_b64_e32 v[42:43], 0
	v_mov_b64_e32 v[44:45], 0
	v_mov_b64_e32 v[46:47], 0
	v_mov_b64_e32 v[56:57], 0
	v_mov_b64_e32 v[58:59], 0
	v_mov_b64_e32 v[60:61], 0
	v_mov_b64_e32 v[62:63], 0
	v_mov_b64_e32 v[64:65], 0
	v_mov_b64_e32 v[66:67], 0
	v_mov_b64_e32 v[68:69], 0
	v_mov_b64_e32 v[70:71], 0
	v_mov_b64_e32 v[80:81], 0
	v_mov_b64_e32 v[82:83], 0
	v_mov_b64_e32 v[84:85], 0
	v_mov_b64_e32 v[86:87], 0
	v_mov_b64_e32 v[96:97], 0
	v_mov_b64_e32 v[98:99], 0
	v_mov_b64_e32 v[100:101], 0
	v_mov_b64_e32 v[102:103], 0
	v_mov_b64_e32 v[112:113], 0
	v_mov_b64_e32 v[114:115], 0
	v_mov_b64_e32 v[116:117], 0
	v_mov_b64_e32 v[118:119], 0
	v_mov_b64_e32 v[72:73], 0
	v_mov_b64_e32 v[74:75], 0
	v_mov_b64_e32 v[76:77], 0
	v_mov_b64_e32 v[78:79], 0
	v_mov_b64_e32 v[88:89], 0
	v_mov_b64_e32 v[90:91], 0
	v_mov_b64_e32 v[92:93], 0
	v_mov_b64_e32 v[94:95], 0
	v_mov_b64_e32 v[104:105], 0
	v_mov_b64_e32 v[106:107], 0
	v_mov_b64_e32 v[108:109], 0
	v_mov_b64_e32 v[110:111], 0
	v_mov_b64_e32 v[120:121], 0
	v_mov_b64_e32 v[122:123], 0
	v_mov_b64_e32 v[124:125], 0
	v_mov_b64_e32 v[126:127], 0
